# phase-C w_in conversion path: 32 row loads back to back with one wait (was 4 batches with interior waits)
# speedup vs baseline: 1.0004x; 1.0004x over previous
; __device__ __forceinline__ void transpose_item(const float* W, int K, int N, int NP, bf16* WT, LAS float* scr, int item, int lane, const LAS float* tab, long long* bias, int ldb, const float* kscale = nullptr) {
;     const int nblk = NP / 32, kb = item / nblk, nb = item - kb * nblk, k0 = 64 * kb, n0 = 32 * nb;
;     const int n = n0 + (lane & 31); const bool okn = n < N;
;     float wv_[32];
;     const float* wp = W + (size_t)(k0 + (lane >> 5)) * N + (okn ? n : 0);
; #pragma unroll
;     for (int i = 0; i < 32; ++i) wv_[i] = wp[(size_t)(2 * i) * N];
.LBB0_286:
	s_andn2_b64 vcc, exec, s[4:5]
	s_cbranch_vccnz .LBB0_148
	s_mul_hi_i32 s4, s24, 0x88888889
	s_add_i32 s4, s4, s24
	s_lshr_b32 s5, s4, 31
	s_ashr_i32 s7, s4, 6
	s_add_i32 s7, s7, s5
	s_lshl_b32 s6, s7, 6
	s_mul_i32 s31, s7, 0xfffff100
	v_or_b32_e32 v1, s6, v45
	v_mov_b64_e32 v[4:5], s[96:97]
	s_movk_i32 s4, 0x3940
	s_add_i32 s31, s31, s28
	v_mad_i64_i32 v[4:5], s[4:5], v1, s4, v[4:5]
	v_add_u32_e32 v2, s31, v64
	s_movk_i32 s4, 0xe50
	v_cmp_gt_i32_e32 vcc, s4, v2
	s_movk_i32 s4, 0x7000
	v_add_u32_e32 v94, 0x1c00, v47
	v_cndmask_b32_e32 v6, 0, v2, vcc
	v_ashrrev_i32_e32 v7, 31, v6
	v_lshl_add_u64 v[4:5], v[6:7], 2, v[4:5]
	v_add_co_u32_e64 v6, s[4:5], s4, v4
	s_nop 1
	v_addc_co_u32_e64 v7, s[4:5], 0, v5, s[4:5]
	v_add_co_u32_e64 v8, s[4:5], s80, v4
	s_nop 1
	v_addc_co_u32_e64 v9, s[4:5], 0, v5, s[4:5]
	s_mov_b32 s4, 0x15000
	s_nop 0
	v_add_co_u32_e64 v10, s[4:5], s4, v4
	s_nop 1
	v_addc_co_u32_e64 v11, s[4:5], 0, v5, s[4:5]
	v_add_co_u32_e64 v12, s[4:5], s15, v4
	s_nop 1
	v_addc_co_u32_e64 v13, s[4:5], 0, v5, s[4:5]
	s_mov_b32 s4, 0x23000
	s_nop 0
	v_add_co_u32_e64 v14, s[4:5], s4, v4
	s_nop 1
	v_addc_co_u32_e64 v15, s[4:5], 0, v5, s[4:5]
	v_add_co_u32_e64 v16, s[4:5], s83, v4
	s_nop 1
	v_addc_co_u32_e64 v17, s[4:5], 0, v5, s[4:5]
	s_mov_b32 s4, 0x32000
	s_nop 0
	v_add_co_u32_e64 v18, s[4:5], s4, v4
	s_nop 1
	v_addc_co_u32_e64 v19, s[4:5], 0, v5, s[4:5]
	s_mov_b32 s4, 0x39000
	global_load_dword v3, v[4:5], off
	global_load_dword v43, v[6:7], off offset:640
	global_load_dword v42, v[8:9], off offset:1280
	global_load_dword v32, v[10:11], off offset:1920
	global_load_dword v31, v[12:13], off offset:2560
	global_load_dword v30, v[14:15], off offset:3200
	global_load_dword v29, v[16:17], off offset:3840
	global_load_dword v28, v[18:19], off offset:384
	v_add_co_u32_e64 v6, s[4:5], s4, v4
	s_nop 1
	v_addc_co_u32_e64 v7, s[4:5], 0, v5, s[4:5]
	v_add_co_u32_e64 v8, s[4:5], s79, v4
	s_nop 1
	v_addc_co_u32_e64 v9, s[4:5], 0, v5, s[4:5]
	s_mov_b32 s4, 0x47000
	s_nop 0
	v_add_co_u32_e64 v10, s[4:5], s4, v4
	s_nop 1
	v_addc_co_u32_e64 v11, s[4:5], 0, v5, s[4:5]
	s_mov_b32 s4, 0x4e000
	s_nop 0
	v_add_co_u32_e64 v12, s[4:5], s4, v4
	s_nop 1
	v_addc_co_u32_e64 v13, s[4:5], 0, v5, s[4:5]
	s_mov_b32 s4, 0x55000
	s_nop 0
	v_add_co_u32_e64 v14, s[4:5], s4, v4
	s_nop 1
	v_addc_co_u32_e64 v15, s[4:5], 0, v5, s[4:5]
	s_mov_b32 s4, 0x5d000
	s_nop 0
	v_add_co_u32_e64 v16, s[4:5], s4, v4
	s_nop 0
	s_nop 0
	v_addc_co_u32_e64 v17, s[4:5], 0, v5, s[4:5]
	s_mov_b32 s4, 0x64000
	s_nop 0
	v_add_co_u32_e64 v18, s[4:5], s4, v4
	s_nop 0
	s_nop 0
	v_addc_co_u32_e64 v19, s[4:5], 0, v5, s[4:5]
	s_mov_b32 s4, 0x6b000
	s_nop 0
	v_add_co_u32_e64 v20, s[4:5], s4, v4
	s_nop 0
	s_nop 0
	v_addc_co_u32_e64 v21, s[4:5], 0, v5, s[4:5]
	s_mov_b32 s4, 0x72000
	global_load_dword v27, v[6:7], off offset:1024
	global_load_dword v26, v[8:9], off offset:1664
	global_load_dword v25, v[10:11], off offset:2304
	global_load_dword v24, v[12:13], off offset:2944
	global_load_dword v23, v[14:15], off offset:3584
	global_load_dword v22, v[16:17], off offset:128
	global_load_dword v65, v[18:19], off offset:768
	global_load_dword v66, v[20:21], off offset:1408
	v_add_co_u32_e64 v6, s[4:5], s4, v4
	s_nop 0
	s_nop 0
	v_addc_co_u32_e64 v7, s[4:5], 0, v5, s[4:5]
	s_mov_b32 s4, 0x79000
	s_nop 0
	v_add_co_u32_e64 v8, s[4:5], s4, v4
	s_nop 0
	s_nop 0
	v_addc_co_u32_e64 v9, s[4:5], 0, v5, s[4:5]
	v_add_co_u32_e64 v10, s[4:5], s14, v4
	s_nop 0
	s_nop 0
	v_addc_co_u32_e64 v11, s[4:5], 0, v5, s[4:5]
	s_mov_b32 s4, 0x87000
	s_nop 0
	v_add_co_u32_e64 v12, s[4:5], s4, v4
	s_nop 0
	s_nop 0
	v_addc_co_u32_e64 v13, s[4:5], 0, v5, s[4:5]
	s_mov_b32 s4, 0x8f000
	s_nop 0
	v_add_co_u32_e64 v14, s[4:5], s4, v4
	s_nop 0
	s_nop 0
	v_addc_co_u32_e64 v15, s[4:5], 0, v5, s[4:5]
	s_mov_b32 s4, 0x96000
	s_nop 0
	v_add_co_u32_e64 v16, s[4:5], s4, v4
	s_nop 0
	s_nop 0
	v_addc_co_u32_e64 v17, s[4:5], 0, v5, s[4:5]
	s_mov_b32 s4, 0x9d000
	s_nop 0
	v_add_co_u32_e64 v18, s[4:5], s4, v4
	s_nop 0
	s_nop 0
	v_addc_co_u32_e64 v19, s[4:5], 0, v5, s[4:5]
	s_mov_b32 s4, 0xa4000
	s_nop 0
	v_add_co_u32_e64 v20, s[4:5], s4, v4
	s_nop 1
	v_addc_co_u32_e64 v21, s[4:5], 0, v5, s[4:5]
	s_mov_b32 s4, 0xab000
	global_load_dword v67, v[6:7], off offset:2048
	global_load_dword v68, v[8:9], off offset:2688
	global_load_dword v69, v[10:11], off offset:3328
	global_load_dword v70, v[12:13], off offset:3968
	s_nop 0
	global_load_dword v14, v[14:15], off offset:512
	s_nop 0
	global_load_dword v15, v[16:17], off offset:1152
	s_nop 0
	global_load_dword v16, v[18:19], off offset:1792
	global_load_dword v17, v[20:21], off offset:2432
	v_add_co_u32_e64 v6, s[4:5], s4, v4
	s_nop 1
	v_addc_co_u32_e64 v7, s[4:5], 0, v5, s[4:5]
	s_mov_b32 s4, 0xb2000
	s_nop 0
	v_add_co_u32_e64 v8, s[4:5], s4, v4
	s_nop 1
	v_addc_co_u32_e64 v9, s[4:5], 0, v5, s[4:5]
	s_mov_b32 s4, 0xba000
	global_load_dword v18, v[6:7], off offset:3072
	global_load_dword v19, v[8:9], off offset:3712
	v_add_co_u32_e64 v6, s[4:5], s4, v4
	s_nop 1
	v_addc_co_u32_e64 v7, s[4:5], 0, v5, s[4:5]
	s_mov_b32 s4, 0xc1000
	s_nop 0
	v_add_co_u32_e64 v8, s[4:5], s4, v4
	s_nop 1
	v_addc_co_u32_e64 v9, s[4:5], 0, v5, s[4:5]
	s_mov_b32 s4, 0xc8000
	s_nop 0
	v_add_co_u32_e64 v10, s[4:5], s4, v4
	s_nop 1
	v_addc_co_u32_e64 v11, s[4:5], 0, v5, s[4:5]
	s_mov_b32 s4, 0xcf000
	s_nop 0
	v_add_co_u32_e64 v12, s[4:5], s4, v4
	s_nop 1
	v_addc_co_u32_e64 v13, s[4:5], 0, v5, s[4:5]
	s_mov_b32 s4, 0xd6000
	global_load_dword v20, v[6:7], off offset:256
	s_nop 0
	global_load_dword v8, v[8:9], off offset:896
	s_nop 0
	global_load_dword v9, v[10:11], off offset:1536
	s_nop 0
	global_load_dword v10, v[12:13], off offset:2176
	v_add_co_u32_e64 v6, s[4:5], s4, v4
	s_nop 1
	v_addc_co_u32_e64 v7, s[4:5], 0, v5, s[4:5]
	s_mov_b32 s4, 0xdd000
	s_nop 0
	v_add_co_u32_e64 v4, s[4:5], s4, v4
	global_load_dword v1, v[6:7], off offset:2816
	s_nop 0
	v_addc_co_u32_e64 v5, s[4:5], 0, v5, s[4:5]
	global_load_dword v71, v[4:5], off offset:3456
	s_waitcnt vmcnt(0)
; #define LAS __attribute__((address_space(3)))
; __device__ __forceinline__ void transpose_item(const float* W, int K, int N, int NP, bf16* WT, LAS float* scr, int item, int lane, const LAS float* tab, long long* bias, int ldb, const float* kscale = nullptr) {
;     ...
;     for (int i = 0; i < 32; ++i) { if (!okn) wv_[i] = 0.f; if (kscale != nullptr) wv_[i] *= kscale[k0 + 2 * i + (lane >> 5)]; scr[(2 * i + (lane >> 5)) * 33 + (lane & 31)] = wv_[i]; }
;     if (tab != nullptr) {
;         const LAS float* tp = tab + k0 + (lane >> 5);
; #pragma unroll
;         for (int bp = 0; bp < 5; ++bp) { float s = 0.f;
; #pragma unroll
;             for (int i = 0; i < 32; ++i) s += tp[bp * 2048 + 2 * i] * wv_[i];
;             s += __shfl_xor(s, 32);
;             if (lane < 32) atomicAdd((unsigned long long*)(bias + (size_t)bp * ldb + n), (unsigned long long)(long long)(s * 4294967296.f)); }
	v_cndmask_b32_e32 v72, 0, v3, vcc
	v_cndmask_b32_e32 v76, 0, v31, vcc
	v_cndmask_b32_e32 v77, 0, v30, vcc
	v_cndmask_b32_e32 v78, 0, v29, vcc
	v_cndmask_b32_e32 v79, 0, v28, vcc
	v_cndmask_b32_e32 v73, 0, v43, vcc
	v_cndmask_b32_e32 v74, 0, v42, vcc
	v_cndmask_b32_e32 v75, 0, v32, vcc
	v_cndmask_b32_e32 v32, v75, v32, vcc
	v_cndmask_b32_e32 v42, v74, v42, vcc
	v_cndmask_b32_e32 v43, v73, v43, vcc
	v_cndmask_b32_e32 v31, v76, v31, vcc
	v_cndmask_b32_e32 v30, v77, v30, vcc
	v_cndmask_b32_e32 v29, v78, v29, vcc
	v_cndmask_b32_e32 v28, v79, v28, vcc
	v_cndmask_b32_e32 v80, 0, v27, vcc
	v_cndmask_b32_e32 v81, 0, v26, vcc
	v_cndmask_b32_e32 v82, 0, v25, vcc
	v_cndmask_b32_e32 v83, 0, v24, vcc
	v_cndmask_b32_e32 v84, 0, v23, vcc
	v_cndmask_b32_e32 v85, 0, v22, vcc
	v_cndmask_b32_e32 v21, 0, v65, vcc
	v_cndmask_b32_e32 v86, 0, v66, vcc
	v_add_u32_e32 v4, 0x400, v47
	ds_write2_b32 v4, v76, v77 offset0:8 offset1:74
	ds_write2_b32 v4, v78, v79 offset0:140 offset1:206
	v_add_u32_e32 v4, 0x800, v47
	ds_write2_b32 v4, v80, v81 offset0:16 offset1:82
	ds_write2_b32 v4, v82, v83 offset0:148 offset1:214
	v_add_u32_e32 v4, 0xc00, v47
	ds_write2_b32 v4, v84, v85 offset0:24 offset1:90
	ds_write2_b32 v4, v21, v86 offset0:156 offset1:222
	v_add_u32_e32 v4, 0x1000, v47
	ds_write2_b32 v47, v72, v73 offset1:66
	ds_write2_b32 v47, v74, v75 offset0:132 offset1:198
	v_cndmask_b32_e32 v21, v21, v65, vcc
	v_cndmask_b32_e32 v65, v72, v3, vcc
	v_cndmask_b32_e32 v27, v80, v27, vcc
	v_cndmask_b32_e32 v26, v81, v26, vcc
	v_cndmask_b32_e32 v25, v82, v25, vcc
	v_cndmask_b32_e32 v24, v83, v24, vcc
	v_cndmask_b32_e32 v23, v84, v23, vcc
	v_cndmask_b32_e32 v22, v85, v22, vcc
	v_xor_b32_e32 v3, 32, v185
	v_readlane_b32 s4, v254, 53
	s_waitcnt vmcnt(15)
	v_cndmask_b32_e32 v87, 0, v67, vcc
	s_waitcnt vmcnt(14)
	v_cndmask_b32_e32 v88, 0, v68, vcc
	s_waitcnt vmcnt(13)
	v_cndmask_b32_e32 v89, 0, v69, vcc
	s_waitcnt vmcnt(12)
	v_cndmask_b32_e32 v90, 0, v70, vcc
	ds_write2_b32 v4, v87, v88 offset0:32 offset1:98
	ds_write2_b32 v4, v89, v90 offset0:164 offset1:230
	s_waitcnt vmcnt(11)
	v_cndmask_b32_e32 v91, 0, v14, vcc
	s_waitcnt vmcnt(10)
	v_cndmask_b32_e32 v13, 0, v15, vcc
	v_add_u32_e32 v4, 0x1400, v47
	s_waitcnt vmcnt(9)
	v_cndmask_b32_e32 v12, 0, v16, vcc
	s_waitcnt vmcnt(8)
	v_cndmask_b32_e32 v11, 0, v17, vcc
	ds_write2_b32 v4, v91, v13 offset0:40 offset1:106
	ds_write2_b32 v4, v12, v11 offset0:172 offset1:238
	v_add_u32_e32 v4, 0x1800, v47
	v_cndmask_b32_e32 v11, v11, v17, vcc
	v_cndmask_b32_e32 v17, v89, v69, vcc
	v_cndmask_b32_e32 v12, v12, v16, vcc
	v_cndmask_b32_e32 v16, v90, v70, vcc
	v_cndmask_b32_e32 v14, v91, v14, vcc
	s_waitcnt vmcnt(7)
	v_cndmask_b32_e32 v92, 0, v18, vcc
	s_waitcnt vmcnt(6)
	v_cndmask_b32_e32 v93, 0, v19, vcc
	ds_write2_b32 v4, v92, v93 offset0:48 offset1:114
	v_cndmask_b32_e32 v13, v13, v15, vcc
	v_and_b32_e32 v15, 64, v185
	v_add_u32_e32 v15, 64, v15
	v_readlane_b32 s5, v254, 54
	s_waitcnt vmcnt(5)
	v_cndmask_b32_e32 v7, 0, v20, vcc
	s_waitcnt vmcnt(4)
	v_cndmask_b32_e32 v6, 0, v8, vcc
	ds_write2_b32 v4, v7, v6 offset0:180 offset1:246
	s_waitcnt vmcnt(3)
	v_cndmask_b32_e32 v5, 0, v9, vcc
	s_waitcnt vmcnt(2)
	v_cndmask_b32_e32 v4, 0, v10, vcc
	ds_write2_b32 v94, v5, v4 offset0:56 offset1:122
	v_cndmask_b32_e32 v4, v4, v10, vcc
	v_cndmask_b32_e32 v7, v7, v20, vcc
	v_cndmask_b32_e32 v20, v86, v66, vcc
	v_lshl_add_u32 v66, s7, 8, v52
	v_cndmask_b32_e32 v5, v5, v9, vcc
	v_cndmask_b32_e32 v9, v92, v18, vcc
	s_waitcnt vmcnt(1)
	v_cndmask_b32_e32 v95, 0, v1, vcc
	v_cndmask_b32_e32 v18, v88, v68, vcc
	v_cndmask_b32_e32 v6, v6, v8, vcc
	s_waitcnt vmcnt(0)
	v_cndmask_b32_e32 v10, 0, v71, vcc
	ds_write2_b32 v94, v95, v10 offset0:188 offset1:254
	ds_read2_b32 v[68:69], v66 offset1:2
	ds_read2_b32 v[70:71], v66 offset0:4 offset1:6
	ds_read2_b32 v[72:73], v66 offset0:8 offset1:10
	ds_read2_b32 v[74:75], v66 offset0:12 offset1:14
	v_cndmask_b32_e32 v8, v93, v19, vcc
	v_cndmask_b32_e32 v19, v87, v67, vcc
	v_cndmask_b32_e32 v1, v95, v1, vcc
	s_waitcnt lgkmcnt(3)
	v_fma_f32 v67, v68, v65, 0
	v_fmac_f32_e32 v67, v69, v43
	s_waitcnt lgkmcnt(2)
	v_fmac_f32_e32 v67, v70, v42
	v_fmac_f32_e32 v67, v71, v32
	ds_read2_b32 v[68:69], v66 offset0:16 offset1:18
	s_waitcnt lgkmcnt(2)
	v_fmac_f32_e32 v67, v72, v31
	v_fmac_f32_e32 v67, v73, v30
	ds_read2_b32 v[70:71], v66 offset0:20 offset1:22
	s_waitcnt lgkmcnt(2)
	v_fmac_f32_e32 v67, v74, v29
	v_fmac_f32_e32 v67, v75, v28
	ds_read2_b32 v[72:73], v66 offset0:24 offset1:26
	s_waitcnt lgkmcnt(2)
	v_fmac_f32_e32 v67, v68, v27
	v_fmac_f32_e32 v67, v69, v26
	ds_read2_b32 v[68:69], v66 offset0:28 offset1:30
	s_waitcnt lgkmcnt(2)
	v_fmac_f32_e32 v67, v70, v25
	v_fmac_f32_e32 v67, v71, v24
	ds_read2_b32 v[70:71], v66 offset0:32 offset1:34
	s_waitcnt lgkmcnt(2)
	v_fmac_f32_e32 v67, v72, v23
	v_fmac_f32_e32 v67, v73, v22
	ds_read2_b32 v[72:73], v66 offset0:36 offset1:38
	s_waitcnt lgkmcnt(2)
	v_fmac_f32_e32 v67, v68, v21
	v_fmac_f32_e32 v67, v69, v20
	ds_read2_b32 v[68:69], v66 offset0:40 offset1:42
	s_waitcnt lgkmcnt(2)
	v_fmac_f32_e32 v67, v70, v19
	v_fmac_f32_e32 v67, v71, v18
	ds_read2_b32 v[70:71], v66 offset0:44 offset1:46
	s_waitcnt lgkmcnt(2)
	v_fmac_f32_e32 v67, v72, v17
	v_fmac_f32_e32 v67, v73, v16
	ds_read2_b32 v[72:73], v66 offset0:48 offset1:50
	s_waitcnt lgkmcnt(2)
	v_fmac_f32_e32 v67, v68, v14
	v_fmac_f32_e32 v67, v69, v13
	ds_read2_b32 v[68:69], v66 offset0:52 offset1:54
	s_waitcnt lgkmcnt(2)
	v_fmac_f32_e32 v67, v70, v12
	v_fmac_f32_e32 v67, v71, v11
	ds_read2_b32 v[70:71], v66 offset0:56 offset1:58
	s_waitcnt lgkmcnt(2)
	v_fmac_f32_e32 v67, v72, v9
	v_fmac_f32_e32 v67, v73, v8
	ds_read2_b32 v[72:73], v66 offset0:60 offset1:62
	s_waitcnt lgkmcnt(2)
	v_fmac_f32_e32 v67, v68, v7
	v_fmac_f32_e32 v67, v69, v6
	s_waitcnt lgkmcnt(1)
	v_fmac_f32_e32 v67, v70, v5
	v_cmp_lt_i32_e32 vcc, v3, v15
	v_fmac_f32_e32 v67, v71, v4
	s_waitcnt lgkmcnt(0)
	v_fmac_f32_e32 v67, v72, v1
	v_cndmask_b32_e32 v3, v185, v3, vcc
	v_lshlrev_b32_e32 v15, 2, v3
	v_fmac_f32_e32 v67, v10, v73
	ds_bpermute_b32 v68, v15, v67
	v_ashrrev_i32_e32 v3, 31, v2
	v_lshl_add_u64 v[2:3], v[2:3], 3, s[4:5]
	s_and_saveexec_b64 s[4:5], s[2:3]
	s_cbranch_execz .LBB0_289
	s_waitcnt lgkmcnt(0)
	v_add_f32_e32 v67, v67, v68
	v_mul_f32_e32 v67, 0x4f800000, v67
	v_trunc_f32_e32 v67, v67
	v_mul_f32_e64 v68, |v67|, s46
	v_floor_f32_e32 v68, v68
	v_fma_f32 v69, v68, s74, |v67|
	v_cvt_u32_f32_e32 v68, v68
	v_cvt_u32_f32_e32 v69, v69
	v_ashrrev_i32_e32 v67, 31, v67
	v_xor_b32_e32 v70, v68, v67
	v_xor_b32_e32 v68, v69, v67
	v_sub_co_u32_e32 v68, vcc, v68, v67
	s_nop 1
	v_subb_co_u32_e32 v69, vcc, v70, v67, vcc
	global_atomic_add_x2 v[2:3], v[68:69], off
